# v33 + one static s_setprio 1 for waves 0-3 during the attention phase (strategy: static priority raise)
# speedup vs baseline: 1.0006x; 1.0006x over previous
; #define LAS __attribute__((address_space(3)))
; DI int obid() { int t = blockIdx.x; asm volatile("" : "+s"(t)); return t; }
; DI int ogrid() { int t = gridDim.x; asm volatile("" : "+s"(t)); return t; }
; DI unsigned char* opq(unsigned char* p) { asm volatile("" : "+s"(p)); return p; }
; #define P (kparams())
; DI void phase_attn(KP P, LAS unsigned char* lds) {
;   const bf16_t* Q = (const bf16_t*)(opq(P->ws) + OFF_BIG + B_QP); const bf16_t* Kg = (const bf16_t*)(opq(P->ws) + OFF_BIG + B_KK); const bf16_t* VT = (const bf16_t*)(opq(P->ws) + OFF_BIG + B_VT);
;   bf16_t* MIX = (bf16_t*)(opq(P->ws) + OFF_U);
;   for (int j = obid(); j < 256; j += ogrid()) {
;     const int bh = j & 7, pi = j >> 3; const int b = bh >> 2, h = bh & 3;
;     attn_unit(lds, Q, Kg, VT, MIX, b, h, 4 * (64 - pi) - 3, 4, 0);
.LBB0_526:
	s_or_b64 exec, exec, s[58:59]
	s_mov_b64 s[4:5], s[88:89]
	s_waitcnt lgkmcnt(0)
	s_barrier
	s_load_dwordx2 s[4:5], s[4:5], 0x98
	s_mov_b32 s3, s2
	s_waitcnt lgkmcnt(0)
	s_mov_b64 s[8:9], s[4:5]
	s_mov_b64 s[6:7], s[4:5]
	s_mov_b64 s[10:11], s[4:5]
	s_cmpk_gt_i32 s3, 0xff
	s_cbranch_scc1 .LBB0_627
	s_add_u32 s8, s8, 0x12712000
	s_addc_u32 s9, s9, 0
	s_add_u32 s33, s6, 0x15772000
	s_addc_u32 s36, s7, 0
	s_add_u32 s37, s10, 0x187d2000
	s_addc_u32 s42, s11, 0
	s_add_u32 s10, s4, 0x210a000
	s_addc_u32 s11, s5, 0
	s_movk_i32 s43, 0x4040
	v_readfirstlane_b32 s99, v224
	s_mov_b32 s99, 0
	s_mov_b32 s13, 0
	s_movk_i32 s58, 0xffe0
	s_movk_i32 s59, 0x600
	v_mov_b64_e32 v[216:217], s[8:9]
	v_mov_b32_e32 v1, 0
	s_movk_i32 s60, 0x300
	s_movk_i32 s61, 0x90
	s_movk_i32 s62, 0x190
	s_lshr_b32 s99, s99, 8
	s_cmp_eq_u32 s99, 0
	s_cbranch_scc0 .Lprio_skip_1
	s_setprio 1
.Lprio_skip_1:
	s_mov_b64 s[14:15], 0x18000
	s_mov_b32 s63, 0xff800000
	s_movk_i32 s64, 0x80
	s_movk_i32 s65, 0x7f
	v_mov_b32_e32 v226, 0xff800000
	v_mov_b32_e32 v227, 0x600
	s_branch .LBB0_530

; #define LAS __attribute__((address_space(3)))
; DI int otid() { int t = threadIdx.x; asm volatile("" : "+v"(t)); return t; }
; DI unsigned char* opq(unsigned char* p) { asm volatile("" : "+s"(p)); return p; }
; #define P (kparams())
; #define G (ogrid())
; #define bid (obid())
; DI void h3_unit(KP P, int e, LAS unsigned char* lds, int gc, int hp) {
;   const int tid = otid(), wave = tid >> 6, lane = tid & 63, r31 = lane & 31, hh = lane >> 5;
;   const _Float16* LOGF = (const _Float16*)(opq(P->ws) + OFF_BIG + B_LOGF); const bf16_t* VH = (const bf16_t*)(opq(P->ws) + OFF_BIG + B_VH);
;   const bf16_t* QH = (const bf16_t*)(opq(P->ws) + OFF_BIG + B_QH); const bf16_t* GT = (const bf16_t*)(opq(P->ws) + OFF_BIG + B_GT);
;   const bf16_t* ST = (const bf16_t*)(opq(P->ws) + OFF_BIG + B_ST); bf16_t* MIX = (bf16_t*)(opq(P->ws) + OFF_U);
;   const size_t r0 = (size_t)gc * 64;
;   LAS unsigned char* QM = lds; LAS unsigned char* KM = lds + 2 * 64 * QROW; LAS unsigned char* VTL = lds + 4 * 64 * QROW;
;   LAS float* EREF = (LAS float*)(lds + 4 * 64 * QROW + 2 * 128 * HROW); LAS float* RED = EREF + 256;
; template <int layer>
; DI void run_layer(LAS unsigned char* lds, const XcdBarrier& xbar) {
;     ...
;       { phase_attn(P, lds);
;     ...
;         __syncthreads(); phase_attn(P, lds);
;     ...
;         for (int u = bid; u < 1028; u += G) h3_unit(P, e, lds, u >> 1, u & 1);
.LBB0_627:
	s_setprio 0
	s_mov_b32 s3, s2
	s_cmpk_gt_i32 s3, 0x403
	s_cbranch_scc1 .LBB0_640
	s_add_i32 s58, 0, 0x11000
	v_mov_b32_e32 v145, 0
	s_mov_b64 s[6:7], 0xc24a000
	s_mov_b32 s30, 0xc24a000
	s_mov_b32 s31, 0xc24b000
	s_mov_b32 s33, 0xc24c000
	s_mov_b32 s34, 0xc24d000
	s_mov_b32 s35, 0xc24e000
	s_mov_b32 s36, 0xc24f000
	s_mov_b32 s37, 0xc250000
	s_mov_b32 s42, 0xc251000
	s_movk_i32 s43, 0xff
	s_movk_i32 s59, 0x90
	s_waitcnt vmcnt(0)
	v_mov_b32_e32 v166, s58
	s_mov_b32 s60, 0x8000
	s_mov_b32 s61, 0x9000
	s_mov_b32 s62, 0xa000
	s_mov_b32 s63, 0xb000
	s_mov_b32 s64, 0xc000
	s_mov_b32 s65, 0xd000
	s_mov_b32 s66, 0xe000
	s_mov_b32 s67, 0xf000
	s_mov_b32 s68, 0xc2a00000
	s_movk_i32 s69, 0x1000
	s_movk_i32 s70, 0x2000
	s_movk_i32 s71, 0x3000
	s_movk_i32 s72, 0x4000
	s_movk_i32 s73, 0x5000
	s_movk_i32 s76, 0x6000
	s_movk_i32 s77, 0x7000
	s_mov_b64 s[8:9], 0x1a7f2000
	s_mov_b32 s80, 0x1a7f2000
	s_mov_b32 s81, 0x1a7f4000
	s_mov_b64 s[10:11], 0xa20a000
	s_mov_b32 s82, 0xa20a000
	s_movk_i32 s83, 0x110
	s_add_i32 s84, 0, 0x1a400
	v_mov_b32_e32 v167, 0x358637bd
	s_mov_b64 s[12:13], 0x210a000
	s_mov_b32 s85, 0x210a000
	v_mov_b32_e32 v168, 0x42a00000
	v_mbcnt_hi_u32_b32 v169, -1, v225
	s_branch .LBB0_630

; #define LAS __attribute__((address_space(3)))
; DI int obid() { int t = blockIdx.x; asm volatile("" : "+s"(t)); return t; }
; DI int ogrid() { int t = gridDim.x; asm volatile("" : "+s"(t)); return t; }
; DI unsigned char* opq(unsigned char* p) { asm volatile("" : "+s"(p)); return p; }
; #define P (kparams())
; DI void phase_attn(KP P, LAS unsigned char* lds) {
;   const bf16_t* Q = (const bf16_t*)(opq(P->ws) + OFF_BIG + B_QP); const bf16_t* Kg = (const bf16_t*)(opq(P->ws) + OFF_BIG + B_KK); const bf16_t* VT = (const bf16_t*)(opq(P->ws) + OFF_BIG + B_VT);
;   bf16_t* MIX = (bf16_t*)(opq(P->ws) + OFF_U);
;   for (int j = obid(); j < 256; j += ogrid()) {
;     const int bh = j & 7, pi = j >> 3; const int b = bh >> 2, h = bh & 3;
;     attn_unit(lds, Q, Kg, VT, MIX, b, h, 4 * (64 - pi) - 3, 4, 0);
.LBB0_2537:
	s_or_b64 exec, exec, s[58:59]
	s_mov_b64 s[4:5], s[88:89]
	s_waitcnt lgkmcnt(0)
	s_barrier
	s_load_dwordx2 s[4:5], s[4:5], 0x98
	v_readlane_b32 s3, v254, 12
	s_waitcnt lgkmcnt(0)
	s_mov_b64 s[8:9], s[4:5]
	s_mov_b64 s[6:7], s[4:5]
	s_mov_b64 s[10:11], s[4:5]
	s_cmpk_gt_i32 s3, 0xff
	s_cbranch_scc1 .LBB0_2638
	s_add_u32 s8, s8, 0x12712000
	s_addc_u32 s9, s9, 0
	s_add_u32 s33, s6, 0x15772000
	s_addc_u32 s36, s7, 0
	s_add_u32 s37, s10, 0x187d2000
	s_addc_u32 s42, s11, 0
	s_add_u32 s10, s4, 0x210a000
	s_addc_u32 s11, s5, 0
	s_movk_i32 s43, 0x4040
	v_readfirstlane_b32 s99, v224
	s_mov_b32 s99, 0
	s_mov_b32 s13, 0
	s_movk_i32 s58, 0xffe0
	s_movk_i32 s59, 0x600
	v_mov_b64_e32 v[216:217], s[8:9]
	v_mov_b32_e32 v1, 0
	s_movk_i32 s60, 0x300
	s_movk_i32 s61, 0x90
	s_movk_i32 s62, 0x190
	s_lshr_b32 s99, s99, 8
	s_cmp_eq_u32 s99, 0
	s_cbranch_scc0 .Lprio_skip_4
	s_setprio 1

; #define LAS __attribute__((address_space(3)))
; DI int otid() { int t = threadIdx.x; asm volatile("" : "+v"(t)); return t; }
; DI unsigned char* opq(unsigned char* p) { asm volatile("" : "+s"(p)); return p; }
; #define P (kparams())
; #define G (ogrid())
; #define bid (obid())
; DI void h3_unit(KP P, int e, LAS unsigned char* lds, int gc, int hp) {
;   const int tid = otid(), wave = tid >> 6, lane = tid & 63, r31 = lane & 31, hh = lane >> 5;
;   const _Float16* LOGF = (const _Float16*)(opq(P->ws) + OFF_BIG + B_LOGF); const bf16_t* VH = (const bf16_t*)(opq(P->ws) + OFF_BIG + B_VH);
;   const bf16_t* QH = (const bf16_t*)(opq(P->ws) + OFF_BIG + B_QH); const bf16_t* GT = (const bf16_t*)(opq(P->ws) + OFF_BIG + B_GT);
;   const bf16_t* ST = (const bf16_t*)(opq(P->ws) + OFF_BIG + B_ST); bf16_t* MIX = (bf16_t*)(opq(P->ws) + OFF_U);
;   const size_t r0 = (size_t)gc * 64;
;   LAS unsigned char* QM = lds; LAS unsigned char* KM = lds + 2 * 64 * QROW; LAS unsigned char* VTL = lds + 4 * 64 * QROW;
;   LAS float* EREF = (LAS float*)(lds + 4 * 64 * QROW + 2 * 128 * HROW); LAS float* RED = EREF + 256;
; template <int layer>
; DI void run_layer(LAS unsigned char* lds, const XcdBarrier& xbar) {
;     ...
;       { phase_attn(P, lds);
;     ...
;         __syncthreads(); phase_attn(P, lds);
;     ...
;         for (int u = bid; u < 1028; u += G) h3_unit(P, e, lds, u >> 1, u & 1);
.LBB0_2638:
	s_setprio 0
	v_readlane_b32 s3, v254, 12
	s_cmpk_gt_i32 s3, 0x403
	s_cbranch_scc1 .LBB0_2651
	s_add_i32 s58, 0, 0x11000
	v_mov_b32_e32 v145, 0
	s_mov_b64 s[6:7], 0xc24a000
	s_mov_b32 s30, 0xc24a000
	s_mov_b32 s31, 0xc24b000
	s_mov_b32 s33, 0xc24c000
	s_mov_b32 s34, 0xc24d000
	s_mov_b32 s35, 0xc24e000
	s_mov_b32 s36, 0xc24f000
	s_mov_b32 s37, 0xc250000
	s_mov_b32 s42, 0xc251000
	s_movk_i32 s43, 0xff
	s_movk_i32 s59, 0x90
	s_waitcnt vmcnt(0)
	v_mov_b32_e32 v166, s58
	s_mov_b32 s60, 0x8000
	s_mov_b32 s61, 0x9000
	s_mov_b32 s62, 0xa000
	s_mov_b32 s63, 0xb000
	s_mov_b32 s64, 0xc000
	s_mov_b32 s65, 0xd000
	s_mov_b32 s66, 0xe000
	s_mov_b32 s67, 0xf000
	s_mov_b32 s68, 0xc2a00000
	s_movk_i32 s69, 0x1000
	s_movk_i32 s70, 0x2000
	s_movk_i32 s71, 0x3000
	s_movk_i32 s72, 0x4000
	s_movk_i32 s73, 0x5000
	s_movk_i32 s74, 0x6000
	s_movk_i32 s75, 0x7000
	s_mov_b64 s[8:9], 0x1a7f2000
	s_mov_b32 s76, 0x1a7f2000
	s_mov_b32 s77, 0x1a7f4000
	s_mov_b64 s[10:11], 0xa20a000
	s_mov_b32 s81, 0xa20a000
	s_movk_i32 s82, 0x110
	s_add_i32 s83, 0, 0x1a400
	v_mov_b32_e32 v167, 0x358637bd
	s_mov_b64 s[12:13], 0x210a000
	s_mov_b32 s84, 0x210a000
	v_mov_b32_e32 v168, 0x42a00000
	s_branch .LBB0_2641
